# WIN GEMM epilogue: the 8 per-row sum-of-squares loads issued together up front (one exposed memory round trip instead of eight per tile)
# speedup vs baseline: 1.0028x; 1.0028x over previous
;   DI void operator()(const f32x4 (&acc)[2][2][4][2], const Unit& u, int wr, int wc, int fr, int fq) const {
;     ...
; #pragma unroll
;       for (int ai = 0; ai < 2; ++ai)
; #pragma unroll
;         for (int m = 0; m < 4; ++m) {
;           const int rowl = rowl0 + ai * 128 + m * 16;
;           const float rstd = rsqrtf(ssq[row_off + rowl] * (1.f / DM) + EPSN) * (mode == 1 ? QSCALE : 1.f);
; #pragma unroll
;           for (int bj = 0; bj < 2; ++bj) {
;             const int col = bj * 128 + c8;
;             if (tl == 19 && col >= 64) continue;
;             f32x4 v0 = acc[ai][bj][m][0] * rstd, v1 = acc[ai][bj][m][1] * rstd;
.LBB0_651:
	v_readlane_b32 s2, v255, 32
	v_ashrrev_i32_e32 v147, 31, v158
	v_mul_lo_u32 v159, s36, v147
	v_add_u32_e32 v144, s2, v158
	v_ashrrev_i32_e32 v145, 31, v144
	v_lshl_add_u64 v[144:145], v[144:145], 2, s[4:5]
	global_load_dword v174, v[144:145], off offset:64
	global_load_dword v175, v[144:145], off offset:128
	global_load_dword v176, v[144:145], off offset:192
	global_load_dword v177, v[144:145], off offset:512
	global_load_dword v178, v[144:145], off offset:576
	global_load_dword v179, v[144:145], off offset:640
	global_load_dword v180, v[144:145], off offset:704
	global_load_dword v146, v[144:145], off
	s_xor_b64 s[10:11], s[10:11], -1
	s_cmp_lg_u32 s0, 19
	s_cselect_b64 s[40:41], -1, 0
	s_cmp_eq_u32 s0, 19
	s_cselect_b64 s[54:55], -1, 0
	s_ashr_i32 s15, s14, 31
	v_mad_u64_u32 v[144:145], s[38:39], s36, v158, 0
	s_lshl_b64 s[14:15], s[14:15], 1
	s_add_u32 s38, s12, s14
	v_mul_lo_u32 v148, s37, v158
	s_addc_u32 s39, s13, s15
	s_and_b64 s[14:15], s[54:55], s[22:23]
	v_cndmask_b32_e64 v149, 0, 1, s[10:11]
	v_add3_u32 v145, v145, v159, v148
	s_and_b64 s[12:13], exec, s[14:15]
	v_cmp_ne_u32_e64 s[10:11], 1, v149
	v_lshl_add_u64 v[144:145], v[144:145], 1, s[38:39]
	s_waitcnt vmcnt(0)
	v_fmamk_f32 v146, v146, 0x3a800000, v203
	v_mul_f32_e32 v147, 0x4b800000, v146
	v_cmp_gt_f32_e32 vcc, s82, v146
	s_nop 1
	v_cndmask_b32_e32 v146, v146, v147, vcc
	v_rsq_f32_e32 v146, v146
	s_nop 0
	v_mul_f32_e32 v147, 0x45800000, v146
	v_cndmask_b32_e32 v146, v146, v147, vcc
	v_mul_f32_e32 v146, s3, v146
	v_mov_b32_e32 v147, v146
	s_mov_b64 vcc, s[12:13]
	s_cbranch_vccnz .LBB0_657
	v_mov_b32_e32 v150, v146
	v_mov_b32_e32 v151, v146
	v_pk_mul_f32 v[148:149], v[126:127], v[150:151]
	v_pk_mul_f32 v[152:153], v[124:125], v[146:147]
	v_pk_mul_f32 v[150:151], v[122:123], v[150:151]
	v_pk_mul_f32 v[154:155], v[120:121], v[146:147]
	s_and_b64 vcc, exec, s[10:11]
	s_mov_b64 s[12:13], -1
	s_cbranch_vccnz .LBB0_654
	s_mov_b64 s[12:13], 0

;   DI void operator()(const f32x4 (&acc)[2][2][4][2], const Unit& u, int wr, int wc, int fr, int fq) const {
;     ...
;         for (int m = 0; m < 4; ++m) {
;           const int rowl = rowl0 + ai * 128 + m * 16;
;           const float rstd = rsqrtf(ssq[row_off + rowl] * (1.f / DM) + EPSN) * (mode == 1 ? QSCALE : 1.f);
; #pragma unroll
;           for (int bj = 0; bj < 2; ++bj) {
;             const int col = bj * 128 + c8;
;             if (tl == 19 && col >= 64) continue;
;             f32x4 v0 = acc[ai][bj][m][0] * rstd, v1 = acc[ai][bj][m][1] * rstd;
.LBB0_663:
	v_or_b32_e32 v148, 16, v158
	v_readlane_b32 s2, v255, 32
	s_xor_b64 s[40:41], s[14:15], -1
	v_mul_lo_u32 v149, s37, v148
	v_add_u32_e32 v144, s2, v148
	v_ashrrev_i32_e32 v145, 31, v144
	v_lshl_add_u64 v[144:145], v[144:145], 2, s[4:5]
	v_mov_b32_e32 v144, v174
	v_fmamk_f32 v144, v144, 0x3a800000, v203
	v_cmp_gt_f32_e32 vcc, s82, v144
	v_mul_f32_e32 v145, 0x4b800000, v144
	s_nop 0
	v_cndmask_b32_e32 v144, v144, v145, vcc
	v_rsq_f32_e32 v144, v144
	s_nop 0
	v_mul_f32_e32 v145, 0x45800000, v144
	v_cndmask_b32_e32 v144, v144, v145, vcc
	v_mul_f32_e32 v146, s3, v144
	v_mad_u64_u32 v[144:145], s[14:15], s36, v148, 0
	v_add3_u32 v145, v145, v159, v149
	v_cndmask_b32_e64 v148, 0, 1, s[40:41]
	v_mov_b32_e32 v147, v146
	v_lshl_add_u64 v[144:145], v[144:145], 1, s[38:39]
	v_cmp_ne_u32_e64 s[14:15], 1, v148
	s_andn2_b64 vcc, exec, s[40:41]
	s_cbranch_vccnz .LBB0_669
	v_mov_b32_e32 v150, v146
	v_mov_b32_e32 v151, v146
	v_pk_mul_f32 v[148:149], v[110:111], v[150:151]
	v_pk_mul_f32 v[152:153], v[108:109], v[146:147]
	v_pk_mul_f32 v[150:151], v[106:107], v[150:151]
	v_pk_mul_f32 v[154:155], v[104:105], v[146:147]
	s_and_b64 vcc, exec, s[10:11]
	s_mov_b64 s[40:41], -1
	s_cbranch_vccnz .LBB0_666
	s_mov_b64 s[40:41], 0

;   DI void operator()(const f32x4 (&acc)[2][2][4][2], const Unit& u, int wr, int wc, int fr, int fq) const {
;     ...
;         for (int m = 0; m < 4; ++m) {
;           const int rowl = rowl0 + ai * 128 + m * 16;
;           const float rstd = rsqrtf(ssq[row_off + rowl] * (1.f / DM) + EPSN) * (mode == 1 ? QSCALE : 1.f);
; #pragma unroll
;           for (int bj = 0; bj < 2; ++bj) {
;             const int col = bj * 128 + c8;
;             if (tl == 19 && col >= 64) continue;
;             f32x4 v0 = acc[ai][bj][m][0] * rstd, v1 = acc[ai][bj][m][1] * rstd;
.LBB0_675:
	v_or_b32_e32 v148, 32, v158
	v_readlane_b32 s2, v255, 32
	v_mul_lo_u32 v149, s37, v148
	s_nop 0
	v_add_u32_e32 v144, s2, v148
	v_ashrrev_i32_e32 v145, 31, v144
	v_lshl_add_u64 v[144:145], v[144:145], 2, s[4:5]
	v_mov_b32_e32 v144, v175
	v_fmamk_f32 v144, v144, 0x3a800000, v203
	v_cmp_gt_f32_e32 vcc, s82, v144
	v_mul_f32_e32 v145, 0x4b800000, v144
	s_nop 0
	v_cndmask_b32_e32 v144, v144, v145, vcc
	v_rsq_f32_e32 v144, v144
	s_nop 0
	v_mul_f32_e32 v145, 0x45800000, v144
	v_cndmask_b32_e32 v144, v144, v145, vcc
	v_mul_f32_e32 v146, s3, v144
	v_mad_u64_u32 v[144:145], s[40:41], s36, v148, 0
	v_add3_u32 v145, v145, v159, v149
	v_mov_b32_e32 v147, v146
	v_lshl_add_u64 v[144:145], v[144:145], 1, s[38:39]
	s_and_b64 vcc, exec, s[14:15]
	s_cbranch_vccnz .LBB0_681
	v_mov_b32_e32 v150, v146
	v_mov_b32_e32 v151, v146
	v_pk_mul_f32 v[148:149], v[94:95], v[150:151]
	v_pk_mul_f32 v[152:153], v[92:93], v[146:147]
	v_pk_mul_f32 v[150:151], v[90:91], v[150:151]
	v_pk_mul_f32 v[154:155], v[88:89], v[146:147]
	s_and_b64 vcc, exec, s[10:11]
	s_mov_b64 s[40:41], -1
	s_cbranch_vccnz .LBB0_678
	s_mov_b64 s[40:41], 0

;   DI void operator()(const f32x4 (&acc)[2][2][4][2], const Unit& u, int wr, int wc, int fr, int fq) const {
;     ...
;         for (int m = 0; m < 4; ++m) {
;           const int rowl = rowl0 + ai * 128 + m * 16;
;           const float rstd = rsqrtf(ssq[row_off + rowl] * (1.f / DM) + EPSN) * (mode == 1 ? QSCALE : 1.f);
; #pragma unroll
;           for (int bj = 0; bj < 2; ++bj) {
;             const int col = bj * 128 + c8;
;             if (tl == 19 && col >= 64) continue;
;             f32x4 v0 = acc[ai][bj][m][0] * rstd, v1 = acc[ai][bj][m][1] * rstd;
.LBB0_687:
	v_or_b32_e32 v148, 48, v158
	v_readlane_b32 s2, v255, 32
	v_mul_lo_u32 v149, s37, v148
	s_nop 0
	v_add_u32_e32 v144, s2, v148
	v_ashrrev_i32_e32 v145, 31, v144
	v_lshl_add_u64 v[144:145], v[144:145], 2, s[4:5]
	v_mov_b32_e32 v144, v176
	v_fmamk_f32 v144, v144, 0x3a800000, v203
	v_cmp_gt_f32_e32 vcc, s82, v144
	v_mul_f32_e32 v145, 0x4b800000, v144
	s_nop 0
	v_cndmask_b32_e32 v144, v144, v145, vcc
	v_rsq_f32_e32 v144, v144
	s_nop 0
	v_mul_f32_e32 v145, 0x45800000, v144
	v_cndmask_b32_e32 v144, v144, v145, vcc
	v_mul_f32_e32 v146, s3, v144
	v_mad_u64_u32 v[144:145], s[40:41], s36, v148, 0
	v_add3_u32 v145, v145, v159, v149
	v_mov_b32_e32 v147, v146
	v_lshl_add_u64 v[144:145], v[144:145], 1, s[38:39]
	s_and_b64 vcc, exec, s[14:15]
	s_cbranch_vccnz .LBB0_693
	v_mov_b32_e32 v150, v146
	v_mov_b32_e32 v151, v146
	v_pk_mul_f32 v[148:149], v[78:79], v[150:151]
	v_pk_mul_f32 v[152:153], v[76:77], v[146:147]
	v_pk_mul_f32 v[150:151], v[74:75], v[150:151]
	v_pk_mul_f32 v[154:155], v[72:73], v[146:147]
	s_and_b64 vcc, exec, s[10:11]
	s_mov_b64 s[40:41], -1
	s_cbranch_vccnz .LBB0_690
	s_mov_b64 s[40:41], 0

;   DI void operator()(const f32x4 (&acc)[2][2][4][2], const Unit& u, int wr, int wc, int fr, int fq) const {
;     ...
;         for (int m = 0; m < 4; ++m) {
;           const int rowl = rowl0 + ai * 128 + m * 16;
;           const float rstd = rsqrtf(ssq[row_off + rowl] * (1.f / DM) + EPSN) * (mode == 1 ? QSCALE : 1.f);
; #pragma unroll
;           for (int bj = 0; bj < 2; ++bj) {
;             const int col = bj * 128 + c8;
;             if (tl == 19 && col >= 64) continue;
;             f32x4 v0 = acc[ai][bj][m][0] * rstd, v1 = acc[ai][bj][m][1] * rstd;
.LBB0_699:
	v_add_u32_e32 v148, 0x80, v158
	v_readlane_b32 s2, v255, 32
	v_mul_lo_u32 v150, s37, v148
	s_nop 0
	v_add_u32_e32 v144, s2, v148
	v_ashrrev_i32_e32 v145, 31, v144
	v_lshl_add_u64 v[144:145], v[144:145], 2, s[4:5]
	v_mov_b32_e32 v144, v177
	v_fmamk_f32 v144, v144, 0x3a800000, v203
	v_cmp_gt_f32_e32 vcc, s82, v144
	v_mul_f32_e32 v145, 0x4b800000, v144
	s_nop 0
	v_cndmask_b32_e32 v144, v144, v145, vcc
	v_rsq_f32_e32 v144, v144
	s_nop 0
	v_mul_f32_e32 v145, 0x45800000, v144
	v_cndmask_b32_e32 v144, v144, v145, vcc
	v_mul_f32_e32 v146, s3, v144
	v_ashrrev_i32_e32 v144, 31, v148
	v_mul_lo_u32 v149, s36, v144
	v_mad_u64_u32 v[144:145], s[40:41], s36, v148, 0
	v_add3_u32 v145, v145, v149, v150
	v_mov_b32_e32 v147, v146
	v_lshl_add_u64 v[144:145], v[144:145], 1, s[38:39]
	s_and_b64 vcc, exec, s[14:15]
	s_cbranch_vccnz .LBB0_705
	v_mov_b32_e32 v150, v146
	v_mov_b32_e32 v151, v146
	v_pk_mul_f32 v[148:149], v[62:63], v[150:151]
	v_pk_mul_f32 v[152:153], v[60:61], v[146:147]
	v_pk_mul_f32 v[150:151], v[58:59], v[150:151]
	v_pk_mul_f32 v[154:155], v[56:57], v[146:147]
	s_and_b64 vcc, exec, s[10:11]
	s_mov_b64 s[40:41], -1
	s_cbranch_vccnz .LBB0_702
	s_mov_b64 s[40:41], 0

;   DI void operator()(const f32x4 (&acc)[2][2][4][2], const Unit& u, int wr, int wc, int fr, int fq) const {
;     ...
;         for (int m = 0; m < 4; ++m) {
;           const int rowl = rowl0 + ai * 128 + m * 16;
;           const float rstd = rsqrtf(ssq[row_off + rowl] * (1.f / DM) + EPSN) * (mode == 1 ? QSCALE : 1.f);
; #pragma unroll
;           for (int bj = 0; bj < 2; ++bj) {
;             const int col = bj * 128 + c8;
;             if (tl == 19 && col >= 64) continue;
;             f32x4 v0 = acc[ai][bj][m][0] * rstd, v1 = acc[ai][bj][m][1] * rstd;
.LBB0_711:
	v_add_u32_e32 v148, 0x90, v158
	v_readlane_b32 s2, v255, 32
	v_mul_lo_u32 v150, s37, v148
	s_nop 0
	v_add_u32_e32 v144, s2, v148
	v_ashrrev_i32_e32 v145, 31, v144
	v_lshl_add_u64 v[144:145], v[144:145], 2, s[4:5]
	v_mov_b32_e32 v144, v178
	v_fmamk_f32 v144, v144, 0x3a800000, v203
	v_cmp_gt_f32_e32 vcc, s82, v144
	v_mul_f32_e32 v145, 0x4b800000, v144
	s_nop 0
	v_cndmask_b32_e32 v144, v144, v145, vcc
	v_rsq_f32_e32 v144, v144
	s_nop 0
	v_mul_f32_e32 v145, 0x45800000, v144
	v_cndmask_b32_e32 v144, v144, v145, vcc
	v_mul_f32_e32 v146, s3, v144
	v_ashrrev_i32_e32 v144, 31, v148
	v_mul_lo_u32 v149, s36, v144
	v_mad_u64_u32 v[144:145], s[40:41], s36, v148, 0
	v_add3_u32 v145, v145, v149, v150
	v_mov_b32_e32 v147, v146
	v_lshl_add_u64 v[144:145], v[144:145], 1, s[38:39]
	s_and_b64 vcc, exec, s[14:15]
	s_cbranch_vccnz .LBB0_717
	v_mov_b32_e32 v150, v146
	v_mov_b32_e32 v151, v146
	v_pk_mul_f32 v[148:149], v[46:47], v[150:151]
	v_pk_mul_f32 v[152:153], v[44:45], v[146:147]
	v_pk_mul_f32 v[150:151], v[42:43], v[150:151]
	v_pk_mul_f32 v[154:155], v[40:41], v[146:147]
	s_and_b64 vcc, exec, s[10:11]
	s_mov_b64 s[40:41], -1
	s_cbranch_vccnz .LBB0_714
	s_mov_b64 s[40:41], 0

;   DI void operator()(const f32x4 (&acc)[2][2][4][2], const Unit& u, int wr, int wc, int fr, int fq) const {
;     ...
;         for (int m = 0; m < 4; ++m) {
;           const int rowl = rowl0 + ai * 128 + m * 16;
;           const float rstd = rsqrtf(ssq[row_off + rowl] * (1.f / DM) + EPSN) * (mode == 1 ? QSCALE : 1.f);
; #pragma unroll
;           for (int bj = 0; bj < 2; ++bj) {
;             const int col = bj * 128 + c8;
;             if (tl == 19 && col >= 64) continue;
;             f32x4 v0 = acc[ai][bj][m][0] * rstd, v1 = acc[ai][bj][m][1] * rstd;
.LBB0_723:
	v_add_u32_e32 v148, 0xa0, v158
	v_readlane_b32 s2, v255, 32
	v_mul_lo_u32 v150, s37, v148
	s_nop 0
	v_add_u32_e32 v144, s2, v148
	v_ashrrev_i32_e32 v145, 31, v144
	v_lshl_add_u64 v[144:145], v[144:145], 2, s[4:5]
	v_mov_b32_e32 v144, v179
	v_fmamk_f32 v144, v144, 0x3a800000, v203
	v_cmp_gt_f32_e32 vcc, s82, v144
	v_mul_f32_e32 v145, 0x4b800000, v144
	s_nop 0
	v_cndmask_b32_e32 v144, v144, v145, vcc
	v_rsq_f32_e32 v144, v144
	s_nop 0
	v_mul_f32_e32 v145, 0x45800000, v144
	v_cndmask_b32_e32 v144, v144, v145, vcc
	v_mul_f32_e32 v146, s3, v144
	v_ashrrev_i32_e32 v144, 31, v148
	v_mul_lo_u32 v149, s36, v144
	v_mad_u64_u32 v[144:145], s[40:41], s36, v148, 0
	v_add3_u32 v145, v145, v149, v150
	v_mov_b32_e32 v147, v146
	v_lshl_add_u64 v[144:145], v[144:145], 1, s[38:39]
	s_and_b64 vcc, exec, s[14:15]
	s_cbranch_vccnz .LBB0_729
	v_mov_b32_e32 v150, v146
	v_mov_b32_e32 v151, v146
	v_pk_mul_f32 v[148:149], v[30:31], v[150:151]
	v_pk_mul_f32 v[152:153], v[28:29], v[146:147]
	v_pk_mul_f32 v[150:151], v[26:27], v[150:151]
	v_pk_mul_f32 v[154:155], v[24:25], v[146:147]
	s_and_b64 vcc, exec, s[10:11]
	s_mov_b64 s[40:41], -1
	s_cbranch_vccnz .LBB0_726
	s_mov_b64 s[40:41], 0

;   DI void operator()(const f32x4 (&acc)[2][2][4][2], const Unit& u, int wr, int wc, int fr, int fq) const {
;     ...
;         for (int m = 0; m < 4; ++m) {
;           const int rowl = rowl0 + ai * 128 + m * 16;
;           const float rstd = rsqrtf(ssq[row_off + rowl] * (1.f / DM) + EPSN) * (mode == 1 ? QSCALE : 1.f);
; #pragma unroll
;           for (int bj = 0; bj < 2; ++bj) {
;             const int col = bj * 128 + c8;
;             if (tl == 19 && col >= 64) continue;
;             f32x4 v0 = acc[ai][bj][m][0] * rstd, v1 = acc[ai][bj][m][1] * rstd;
.LBB0_735:
	v_add_u32_e32 v146, 0xb0, v158
	v_readlane_b32 s2, v255, 32
	s_and_b64 vcc, exec, s[14:15]
	v_ashrrev_i32_e32 v147, 31, v146
	v_add_u32_e32 v144, s2, v146
	v_ashrrev_i32_e32 v145, 31, v144
	v_lshl_add_u64 v[144:145], v[144:145], 2, s[4:5]
	v_mov_b32_e32 v144, v180
	v_mul_lo_u32 v148, s37, v146
	v_fmamk_f32 v144, v144, 0x3a800000, v203
	v_mul_f32_e32 v145, 0x4b800000, v144
	v_cmp_gt_f32_e64 s[14:15], s82, v144
	s_nop 1
	v_cndmask_b32_e64 v144, v144, v145, s[14:15]
	v_rsq_f32_e32 v149, v144
	v_mad_u64_u32 v[144:145], s[40:41], s36, v146, 0
	v_mul_lo_u32 v146, s36, v147
	v_add3_u32 v145, v145, v146, v148
	v_mul_f32_e32 v146, 0x45800000, v149
	v_cndmask_b32_e64 v146, v149, v146, s[14:15]
	v_mul_f32_e32 v146, s3, v146
	v_mov_b32_e32 v147, v146
	v_lshl_add_u64 v[144:145], v[144:145], 1, s[38:39]
	s_cbranch_vccnz .LBB0_741
	v_mov_b32_e32 v150, v146
	v_mov_b32_e32 v151, v146
	v_pk_mul_f32 v[148:149], v[14:15], v[150:151]
	v_pk_mul_f32 v[152:153], v[12:13], v[146:147]
	v_pk_mul_f32 v[150:151], v[10:11], v[150:151]
	v_pk_mul_f32 v[154:155], v[8:9], v[146:147]
	s_and_b64 vcc, exec, s[10:11]
	s_mov_b64 s[14:15], -1
	s_cbranch_vccnz .LBB0_738
	s_mov_b64 s[14:15], 0

; DI u32x4 pack8(f32x4 a, f32x4 b) { u32x4 w; w.x = cvtpk(a[0], a[1]); w.y = cvtpk(a[2], a[3]); w.z = cvtpk(b[0], b[1]); w.w = cvtpk(b[2], b[3]); return w; }
;   DI void operator()(const f32x4 (&acc)[2][2][4][2], const Unit& u, int wr, int wc, int fr, int fq) const {
;     ...
; #pragma unroll
;       for (int ai = 0; ai < 2; ++ai)
; #pragma unroll
;         for (int m = 0; m < 4; ++m) {
;           const int rowl = rowl0 + ai * 128 + m * 16; const int t = rowl & (SEQ - 1);
;           const float rstd = rsqrtf(ssq[row_off + rowl] * (1.f / DM) + EPSN) * sc;
;           const float* rc = rope + t * 32 + 8 * fq;
;           const f32x4 c0 = *(const f32x4*)(rc), c1 = *(const f32x4*)(rc + 4), s0 = *(const f32x4*)(rc + 65536), s1 = *(const f32x4*)(rc + 65536 + 4);
;           const f32x4 x1a = acc[ai][0][m][0] * rstd, x1b = acc[ai][0][m][1] * rstd, x2a = acc[ai][1][m][0] * rstd, x2b = acc[ai][1][m][1] * rstd;
;           const f32x4 o1a = x1a * c0 - x2a * s0, o1b = x1b * c1 - x2b * s1, o2a = x2a * c0 + x1a * s0, o2b = x2b * c1 + x1b * s1;
;           bf16_t* d = dst + (size_t)rowl * pitch + colbase + 8 * fq;
;           *(u32x4*)(d) = pack8(o1a, o1b); *(u32x4*)(d + 32) = pack8(o2a, o2b);
;           asm volatile("" ::: "memory");
;         }
.LBB0_756:
	v_readlane_b32 s2, v255, 32
	s_ashr_i32 s13, s12, 31
	s_lshl_b64 s[12:13], s[12:13], 1
	v_add_u32_e32 v146, s2, v158
	v_ashrrev_i32_e32 v147, 31, v146
	v_lshl_add_u64 v[146:147], v[146:147], 2, s[4:5]
	global_load_dword v174, v[146:147], off offset:64
	global_load_dword v175, v[146:147], off offset:128
	global_load_dword v176, v[146:147], off offset:192
	global_load_dword v177, v[146:147], off offset:512
	global_load_dword v178, v[146:147], off offset:576
	global_load_dword v179, v[146:147], off offset:640
	global_load_dword v180, v[146:147], off offset:704
	global_load_dword v146, v[146:147], off
	s_add_u32 s12, s14, s12
	s_addc_u32 s13, s15, s13
	s_mov_b64 s[14:15], 0x40000
	s_mov_b32 s0, 0x40000
	v_lshl_add_u64 v[144:145], s[12:13], 0, v[186:187]
	s_waitcnt vmcnt(0)
	v_fmamk_f32 v146, v146, 0x3a800000, v203
	v_cmp_gt_f32_e32 vcc, s82, v146
	v_mul_f32_e32 v147, 0x4b800000, v146
	s_nop 0
	v_cndmask_b32_e32 v146, v146, v147, vcc
	v_rsq_f32_e32 v146, v146
	s_nop 0
	v_mul_f32_e32 v147, 0x45800000, v146
	v_cndmask_b32_e32 v146, v146, v147, vcc
	v_mul_f32_e32 v154, s3, v146
	v_lshlrev_b32_e32 v146, 7, v158
	v_and_b32_e32 v146, 0x3e780, v146
	v_mov_b32_e32 v147, v187
	v_lshl_add_u64 v[160:161], v[138:139], 0, v[146:147]
	global_load_dwordx4 v[146:149], v[160:161], off offset:16
	global_load_dwordx4 v[150:153], v[160:161], off
	v_lshl_add_u64 v[164:165], v[160:161], 0, s[14:15]
	v_add_co_u32_e32 v160, vcc, s0, v160
	v_pk_mul_f32 v[116:117], v[116:117], v[154:155] op_sel_hi:[1,0]
	s_nop 0
	v_addc_co_u32_e32 v161, vcc, 0, v161, vcc
	global_load_dwordx4 v[160:163], v[160:161], off
	s_nop 0
	global_load_dwordx4 v[164:167], v[164:165], off offset:16
	v_pk_mul_f32 v[124:125], v[124:125], v[154:155] op_sel_hi:[1,0]
	v_pk_mul_f32 v[126:127], v[126:127], v[154:155] op_sel_hi:[1,0]
	v_pk_mul_f32 v[120:121], v[120:121], v[154:155] op_sel_hi:[1,0]
	v_pk_mul_f32 v[122:123], v[122:123], v[154:155] op_sel_hi:[1,0]
	v_pk_mul_f32 v[118:119], v[118:119], v[154:155] op_sel_hi:[1,0]
	v_pk_mul_f32 v[114:115], v[114:115], v[154:155] op_sel_hi:[1,0]
	v_pk_mul_f32 v[112:113], v[112:113], v[154:155] op_sel_hi:[1,0]
	s_waitcnt vmcnt(1)
	v_pk_mul_f32 v[154:155], v[160:161], v[116:117]
	s_nop 0
	v_pk_fma_f32 v[154:155], v[150:151], v[124:125], v[154:155] neg_lo:[0,0,1] neg_hi:[0,0,1]
	v_pk_mul_f32 v[124:125], v[160:161], v[124:125]
	s_waitcnt vmcnt(0)
	v_pk_mul_f32 v[170:171], v[164:165], v[112:113]
	v_pk_mul_f32 v[172:173], v[166:167], v[114:115]
	v_pk_fma_f32 v[124:125], v[150:151], v[116:117], v[124:125]
	v_pk_mul_f32 v[116:117], v[164:165], v[120:121]
	v_pk_fma_f32 v[172:173], v[148:149], v[122:123], v[172:173] neg_lo:[0,0,1] neg_hi:[0,0,1]
	v_pk_fma_f32 v[170:171], v[146:147], v[120:121], v[170:171] neg_lo:[0,0,1] neg_hi:[0,0,1]
	v_pk_mul_f32 v[120:121], v[166:167], v[122:123]
	v_pk_fma_f32 v[122:123], v[146:147], v[112:113], v[116:117]
	v_ashrrev_i32_e32 v112, 31, v158
	v_pk_mul_f32 v[168:169], v[162:163], v[118:119]
	v_pk_fma_f32 v[120:121], v[148:149], v[114:115], v[120:121]
	v_mul_lo_u32 v113, s11, v158
	v_mul_lo_u32 v112, s10, v112
	v_mad_u64_u32 v[114:115], s[12:13], s10, v158, 0
	v_pk_fma_f32 v[168:169], v[152:153], v[126:127], v[168:169] neg_lo:[0,0,1] neg_hi:[0,0,1]
	v_pk_mul_f32 v[126:127], v[162:163], v[126:127]
	v_add3_u32 v115, v115, v112, v113
	v_pk_fma_f32 v[118:119], v[152:153], v[118:119], v[126:127]
	v_lshl_add_u64 v[126:127], v[114:115], 1, v[144:145]
	v_cvt_pk_bf16_f32 v114, v154, v155
	v_cvt_pk_bf16_f32 v115, v168, v169
	v_cvt_pk_bf16_f32 v116, v170, v171
	v_cvt_pk_bf16_f32 v117, v172, v173
	global_store_dwordx4 v[126:127], v[114:117], off
	v_or_b32_e32 v113, 16, v158
	s_nop 0
	v_cvt_pk_bf16_f32 v114, v124, v125
	v_cvt_pk_bf16_f32 v115, v118, v119
	v_cvt_pk_bf16_f32 v116, v122, v123
	v_cvt_pk_bf16_f32 v117, v120, v121
	global_store_dwordx4 v[126:127], v[114:117], off offset:64
	s_nop 1
	v_add_u32_e32 v114, s2, v113
	v_ashrrev_i32_e32 v115, 31, v114
	v_lshl_add_u64 v[114:115], v[114:115], 2, s[4:5]
	v_mov_b32_e32 v114, v174
	v_fmamk_f32 v114, v114, 0x3a800000, v203
	v_cmp_gt_f32_e32 vcc, s82, v114
	v_mul_f32_e32 v115, 0x4b800000, v114
	s_nop 0
	v_cndmask_b32_e32 v114, v114, v115, vcc
	v_rsq_f32_e32 v114, v114
	s_nop 0
	v_mul_f32_e32 v115, 0x45800000, v114
	v_cndmask_b32_e32 v114, v114, v115, vcc
	v_mul_f32_e32 v126, s3, v114
	v_lshlrev_b32_e32 v114, 7, v113
	v_and_b32_e32 v114, 0x3ef80, v114
	v_mov_b32_e32 v115, v187
	v_lshl_add_u64 v[122:123], v[138:139], 0, v[114:115]
	global_load_dwordx4 v[114:117], v[122:123], off offset:16
	global_load_dwordx4 v[118:121], v[122:123], off
	v_lshl_add_u64 v[146:147], v[122:123], 0, s[14:15]
	v_add_co_u32_e32 v122, vcc, s0, v122
	v_pk_mul_f32 v[98:99], v[98:99], v[126:127] op_sel_hi:[1,0]
	s_nop 0
	v_addc_co_u32_e32 v123, vcc, 0, v123, vcc
	global_load_dwordx4 v[122:125], v[122:123], off
	s_nop 0
	global_load_dwordx4 v[146:149], v[146:147], off offset:16
	v_pk_mul_f32 v[96:97], v[96:97], v[126:127] op_sel_hi:[1,0]
	v_pk_mul_f32 v[104:105], v[104:105], v[126:127] op_sel_hi:[1,0]
	v_pk_mul_f32 v[106:107], v[106:107], v[126:127] op_sel_hi:[1,0]
	v_pk_mul_f32 v[102:103], v[102:103], v[126:127] op_sel_hi:[1,0]
	v_pk_mul_f32 v[100:101], v[100:101], v[126:127] op_sel_hi:[1,0]
	v_pk_mul_f32 v[108:109], v[108:109], v[126:127] op_sel_hi:[1,0]
	v_pk_mul_f32 v[110:111], v[110:111], v[126:127] op_sel_hi:[1,0]
	s_waitcnt vmcnt(1)
	v_pk_mul_f32 v[126:127], v[122:123], v[100:101]
	s_waitcnt vmcnt(0)
; DI u32x4 pack8(f32x4 a, f32x4 b) { u32x4 w; w.x = cvtpk(a[0], a[1]); w.y = cvtpk(a[2], a[3]); w.z = cvtpk(b[0], b[1]); w.w = cvtpk(b[2], b[3]); return w; }
;   DI void operator()(const f32x4 (&acc)[2][2][4][2], const Unit& u, int wr, int wc, int fr, int fq) const {
;     ...
; #pragma unroll
;       for (int ai = 0; ai < 2; ++ai)
; #pragma unroll
;         for (int m = 0; m < 4; ++m) {
;           const int rowl = rowl0 + ai * 128 + m * 16; const int t = rowl & (SEQ - 1);
;           const float rstd = rsqrtf(ssq[row_off + rowl] * (1.f / DM) + EPSN) * sc;
;           const float* rc = rope + t * 32 + 8 * fq;
;           const f32x4 c0 = *(const f32x4*)(rc), c1 = *(const f32x4*)(rc + 4), s0 = *(const f32x4*)(rc + 65536), s1 = *(const f32x4*)(rc + 65536 + 4);
;           const f32x4 x1a = acc[ai][0][m][0] * rstd, x1b = acc[ai][0][m][1] * rstd, x2a = acc[ai][1][m][0] * rstd, x2b = acc[ai][1][m][1] * rstd;
;           const f32x4 o1a = x1a * c0 - x2a * s0, o1b = x1b * c1 - x2b * s1, o2a = x2a * c0 + x1a * s0, o2b = x2b * c1 + x1b * s1;
;           bf16_t* d = dst + (size_t)rowl * pitch + colbase + 8 * fq;
;           *(u32x4*)(d) = pack8(o1a, o1b); *(u32x4*)(d + 32) = pack8(o2a, o2b);
;           asm volatile("" ::: "memory");
;         }
	v_pk_mul_f32 v[152:153], v[146:147], v[96:97]
	v_pk_mul_f32 v[154:155], v[148:149], v[98:99]
	v_pk_fma_f32 v[152:153], v[114:115], v[104:105], v[152:153] neg_lo:[0,0,1] neg_hi:[0,0,1]
	v_pk_fma_f32 v[154:155], v[116:117], v[106:107], v[154:155] neg_lo:[0,0,1] neg_hi:[0,0,1]
	v_pk_mul_f32 v[104:105], v[146:147], v[104:105]
	v_pk_mul_f32 v[106:107], v[148:149], v[106:107]
	v_pk_mul_f32 v[150:151], v[124:125], v[102:103]
	v_pk_fma_f32 v[106:107], v[116:117], v[98:99], v[106:107]
	v_pk_fma_f32 v[104:105], v[114:115], v[96:97], v[104:105]
	v_mul_lo_u32 v98, s11, v113
	v_mad_u64_u32 v[96:97], s[12:13], s10, v113, 0
	v_pk_fma_f32 v[150:151], v[120:121], v[110:111], v[150:151] neg_lo:[0,0,1] neg_hi:[0,0,1]
	v_pk_fma_f32 v[126:127], v[118:119], v[108:109], v[126:127] neg_lo:[0,0,1] neg_hi:[0,0,1]
	v_pk_mul_f32 v[108:109], v[122:123], v[108:109]
	v_pk_mul_f32 v[110:111], v[124:125], v[110:111]
	v_add3_u32 v97, v97, v112, v98
	v_pk_fma_f32 v[102:103], v[120:121], v[102:103], v[110:111]
	v_pk_fma_f32 v[100:101], v[118:119], v[100:101], v[108:109]
	v_lshl_add_u64 v[108:109], v[96:97], 1, v[144:145]
	v_cvt_pk_bf16_f32 v96, v126, v127
	v_cvt_pk_bf16_f32 v97, v150, v151
	v_cvt_pk_bf16_f32 v98, v152, v153
	v_cvt_pk_bf16_f32 v99, v154, v155
	global_store_dwordx4 v[108:109], v[96:99], off
	v_or_b32_e32 v113, 32, v158
	s_nop 0
	v_cvt_pk_bf16_f32 v96, v100, v101
	v_cvt_pk_bf16_f32 v97, v102, v103
	v_cvt_pk_bf16_f32 v98, v104, v105
	v_cvt_pk_bf16_f32 v99, v106, v107
	global_store_dwordx4 v[108:109], v[96:99], off offset:64
	s_nop 1
	v_add_u32_e32 v96, s2, v113
	v_ashrrev_i32_e32 v97, 31, v96
	v_lshl_add_u64 v[96:97], v[96:97], 2, s[4:5]
	v_mov_b32_e32 v96, v175
	v_fmamk_f32 v96, v96, 0x3a800000, v203
	v_cmp_gt_f32_e32 vcc, s82, v96
	v_mul_f32_e32 v97, 0x4b800000, v96
	s_nop 0
	v_cndmask_b32_e32 v96, v96, v97, vcc
	v_rsq_f32_e32 v96, v96
	s_nop 0
	v_mul_f32_e32 v97, 0x45800000, v96
	v_cndmask_b32_e32 v96, v96, v97, vcc
	v_mul_f32_e32 v114, s3, v96
	v_lshlrev_b32_e32 v96, 7, v113
	v_and_b32_e32 v96, 0x3f780, v96
	v_mov_b32_e32 v97, v187
	v_lshl_add_u64 v[104:105], v[138:139], 0, v[96:97]
	global_load_dwordx4 v[96:99], v[104:105], off offset:16
	global_load_dwordx4 v[100:103], v[104:105], off
	v_lshl_add_u64 v[108:109], v[104:105], 0, s[14:15]
	v_add_co_u32_e32 v104, vcc, s0, v104
	v_pk_mul_f32 v[82:83], v[82:83], v[114:115] op_sel_hi:[1,0]
	s_nop 0
	v_addc_co_u32_e32 v105, vcc, 0, v105, vcc
	global_load_dwordx4 v[104:107], v[104:105], off
	s_nop 0
	global_load_dwordx4 v[108:111], v[108:109], off offset:16
	v_pk_mul_f32 v[80:81], v[80:81], v[114:115] op_sel_hi:[1,0]
	v_pk_mul_f32 v[88:89], v[88:89], v[114:115] op_sel_hi:[1,0]
	v_pk_mul_f32 v[90:91], v[90:91], v[114:115] op_sel_hi:[1,0]
	v_pk_mul_f32 v[86:87], v[86:87], v[114:115] op_sel_hi:[1,0]
	v_pk_mul_f32 v[84:85], v[84:85], v[114:115] op_sel_hi:[1,0]
	v_pk_mul_f32 v[92:93], v[92:93], v[114:115] op_sel_hi:[1,0]
	v_pk_mul_f32 v[94:95], v[94:95], v[114:115] op_sel_hi:[1,0]
	s_waitcnt vmcnt(1)
	v_pk_mul_f32 v[114:115], v[104:105], v[84:85]
	s_waitcnt vmcnt(0)
	v_pk_mul_f32 v[118:119], v[108:109], v[80:81]
	v_pk_mul_f32 v[120:121], v[110:111], v[82:83]
	v_pk_fma_f32 v[118:119], v[96:97], v[88:89], v[118:119] neg_lo:[0,0,1] neg_hi:[0,0,1]
	v_pk_fma_f32 v[120:121], v[98:99], v[90:91], v[120:121] neg_lo:[0,0,1] neg_hi:[0,0,1]
	v_pk_mul_f32 v[88:89], v[108:109], v[88:89]
	v_pk_mul_f32 v[90:91], v[110:111], v[90:91]
	v_pk_mul_f32 v[116:117], v[106:107], v[86:87]
	v_pk_fma_f32 v[90:91], v[98:99], v[82:83], v[90:91]
	v_pk_fma_f32 v[88:89], v[96:97], v[80:81], v[88:89]
	v_mul_lo_u32 v82, s11, v113
	v_mad_u64_u32 v[80:81], s[12:13], s10, v113, 0
	v_pk_fma_f32 v[116:117], v[102:103], v[94:95], v[116:117] neg_lo:[0,0,1] neg_hi:[0,0,1]
	v_pk_fma_f32 v[114:115], v[100:101], v[92:93], v[114:115] neg_lo:[0,0,1] neg_hi:[0,0,1]
	v_pk_mul_f32 v[92:93], v[104:105], v[92:93]
	v_pk_mul_f32 v[94:95], v[106:107], v[94:95]
	v_add3_u32 v81, v81, v112, v82
	v_pk_fma_f32 v[86:87], v[102:103], v[86:87], v[94:95]
	v_pk_fma_f32 v[84:85], v[100:101], v[84:85], v[92:93]
	v_lshl_add_u64 v[92:93], v[80:81], 1, v[144:145]
	v_cvt_pk_bf16_f32 v80, v114, v115
	v_cvt_pk_bf16_f32 v81, v116, v117
	v_cvt_pk_bf16_f32 v82, v118, v119
	v_cvt_pk_bf16_f32 v83, v120, v121
	global_store_dwordx4 v[92:93], v[80:83], off
	v_or_b32_e32 v104, 48, v158
	s_nop 0
	v_cvt_pk_bf16_f32 v80, v84, v85
	v_cvt_pk_bf16_f32 v81, v86, v87
	v_cvt_pk_bf16_f32 v82, v88, v89
	v_cvt_pk_bf16_f32 v83, v90, v91
	global_store_dwordx4 v[92:93], v[80:83], off offset:64
	s_nop 1
	v_add_u32_e32 v80, s2, v104
	v_ashrrev_i32_e32 v81, 31, v80
	v_lshl_add_u64 v[80:81], v[80:81], 2, s[4:5]
	v_mov_b32_e32 v80, v176
	v_fmamk_f32 v80, v80, 0x3a800000, v203
	v_cmp_gt_f32_e32 vcc, s82, v80
	v_mul_f32_e32 v81, 0x4b800000, v80
	s_nop 0
	v_cndmask_b32_e32 v80, v80, v81, vcc
	v_rsq_f32_e32 v80, v80
	s_nop 0
	v_mul_f32_e32 v81, 0x45800000, v80
	v_cndmask_b32_e32 v80, v80, v81, vcc
	v_mul_f32_e32 v96, s3, v80
	v_lshlrev_b32_e32 v80, 7, v104
	v_and_b32_e32 v80, 0x3ff80, v80
	v_mov_b32_e32 v81, v187
	v_lshl_add_u64 v[88:89], v[138:139], 0, v[80:81]
	global_load_dwordx4 v[80:83], v[88:89], off offset:16
	global_load_dwordx4 v[84:87], v[88:89], off
	v_lshl_add_u64 v[92:93], v[88:89], 0, s[14:15]
	v_add_co_u32_e32 v88, vcc, s0, v88
	v_pk_mul_f32 v[66:67], v[66:67], v[96:97] op_sel_hi:[1,0]
	s_nop 0
	v_addc_co_u32_e32 v89, vcc, 0, v89, vcc
	global_load_dwordx4 v[88:91], v[88:89], off
	s_nop 0
	global_load_dwordx4 v[92:95], v[92:93], off offset:16
	v_pk_mul_f32 v[64:65], v[64:65], v[96:97] op_sel_hi:[1,0]
	v_pk_mul_f32 v[72:73], v[72:73], v[96:97] op_sel_hi:[1,0]
	v_pk_mul_f32 v[74:75], v[74:75], v[96:97] op_sel_hi:[1,0]
	v_pk_mul_f32 v[70:71], v[70:71], v[96:97] op_sel_hi:[1,0]
	v_pk_mul_f32 v[68:69], v[68:69], v[96:97] op_sel_hi:[1,0]
	v_pk_mul_f32 v[76:77], v[76:77], v[96:97] op_sel_hi:[1,0]
	v_pk_mul_f32 v[78:79], v[78:79], v[96:97] op_sel_hi:[1,0]
	s_waitcnt vmcnt(1)
; DI u32x4 pack8(f32x4 a, f32x4 b) { u32x4 w; w.x = cvtpk(a[0], a[1]); w.y = cvtpk(a[2], a[3]); w.z = cvtpk(b[0], b[1]); w.w = cvtpk(b[2], b[3]); return w; }
;   DI void operator()(const f32x4 (&acc)[2][2][4][2], const Unit& u, int wr, int wc, int fr, int fq) const {
;     ...
; #pragma unroll
;       for (int ai = 0; ai < 2; ++ai)
; #pragma unroll
;         for (int m = 0; m < 4; ++m) {
;           const int rowl = rowl0 + ai * 128 + m * 16; const int t = rowl & (SEQ - 1);
;           const float rstd = rsqrtf(ssq[row_off + rowl] * (1.f / DM) + EPSN) * sc;
;           const float* rc = rope + t * 32 + 8 * fq;
;           const f32x4 c0 = *(const f32x4*)(rc), c1 = *(const f32x4*)(rc + 4), s0 = *(const f32x4*)(rc + 65536), s1 = *(const f32x4*)(rc + 65536 + 4);
;           const f32x4 x1a = acc[ai][0][m][0] * rstd, x1b = acc[ai][0][m][1] * rstd, x2a = acc[ai][1][m][0] * rstd, x2b = acc[ai][1][m][1] * rstd;
;           const f32x4 o1a = x1a * c0 - x2a * s0, o1b = x1b * c1 - x2b * s1, o2a = x2a * c0 + x1a * s0, o2b = x2b * c1 + x1b * s1;
;           bf16_t* d = dst + (size_t)rowl * pitch + colbase + 8 * fq;
;           *(u32x4*)(d) = pack8(o1a, o1b); *(u32x4*)(d + 32) = pack8(o2a, o2b);
;           asm volatile("" ::: "memory");
;         }
	v_pk_mul_f32 v[96:97], v[88:89], v[68:69]
	s_waitcnt vmcnt(0)
	v_pk_mul_f32 v[100:101], v[92:93], v[64:65]
	v_pk_mul_f32 v[102:103], v[94:95], v[66:67]
	v_pk_fma_f32 v[100:101], v[80:81], v[72:73], v[100:101] neg_lo:[0,0,1] neg_hi:[0,0,1]
	v_pk_fma_f32 v[102:103], v[82:83], v[74:75], v[102:103] neg_lo:[0,0,1] neg_hi:[0,0,1]
	v_pk_mul_f32 v[72:73], v[92:93], v[72:73]
	v_pk_mul_f32 v[74:75], v[94:95], v[74:75]
	v_pk_mul_f32 v[98:99], v[90:91], v[70:71]
	v_pk_fma_f32 v[74:75], v[82:83], v[66:67], v[74:75]
	v_pk_fma_f32 v[72:73], v[80:81], v[64:65], v[72:73]
	v_mul_lo_u32 v66, s11, v104
	v_mad_u64_u32 v[64:65], s[12:13], s10, v104, 0
	v_pk_fma_f32 v[98:99], v[86:87], v[78:79], v[98:99] neg_lo:[0,0,1] neg_hi:[0,0,1]
	v_pk_fma_f32 v[96:97], v[84:85], v[76:77], v[96:97] neg_lo:[0,0,1] neg_hi:[0,0,1]
	v_pk_mul_f32 v[76:77], v[88:89], v[76:77]
	v_pk_mul_f32 v[78:79], v[90:91], v[78:79]
	v_add3_u32 v65, v65, v112, v66
	v_pk_fma_f32 v[70:71], v[86:87], v[70:71], v[78:79]
	v_pk_fma_f32 v[68:69], v[84:85], v[68:69], v[76:77]
	v_lshl_add_u64 v[76:77], v[64:65], 1, v[144:145]
	v_cvt_pk_bf16_f32 v64, v96, v97
	v_cvt_pk_bf16_f32 v65, v98, v99
	v_cvt_pk_bf16_f32 v66, v100, v101
	v_cvt_pk_bf16_f32 v67, v102, v103
	global_store_dwordx4 v[76:77], v[64:67], off
	v_add_u32_e32 v88, 0x80, v158
	s_nop 0
	v_cvt_pk_bf16_f32 v64, v68, v69
	v_cvt_pk_bf16_f32 v65, v70, v71
	v_cvt_pk_bf16_f32 v66, v72, v73
	v_cvt_pk_bf16_f32 v67, v74, v75
	global_store_dwordx4 v[76:77], v[64:67], off offset:64
	s_nop 1
	v_add_u32_e32 v64, s2, v88
	v_ashrrev_i32_e32 v65, 31, v64
	v_lshl_add_u64 v[64:65], v[64:65], 2, s[4:5]
	v_mov_b32_e32 v64, v177
	v_fmamk_f32 v64, v64, 0x3a800000, v203
	v_cmp_gt_f32_e32 vcc, s82, v64
	v_mul_f32_e32 v65, 0x4b800000, v64
	s_nop 0
	v_cndmask_b32_e32 v64, v64, v65, vcc
	v_rsq_f32_e32 v64, v64
	s_nop 0
	v_mul_f32_e32 v65, 0x45800000, v64
	v_cndmask_b32_e32 v64, v64, v65, vcc
	v_mul_f32_e32 v80, s3, v64
	v_lshlrev_b32_e32 v64, 7, v88
	v_and_b32_e32 v64, 0x3e780, v64
	v_mov_b32_e32 v65, v187
	v_lshl_add_u64 v[72:73], v[138:139], 0, v[64:65]
	global_load_dwordx4 v[64:67], v[72:73], off offset:16
	global_load_dwordx4 v[68:71], v[72:73], off
	v_lshl_add_u64 v[76:77], v[72:73], 0, s[14:15]
	v_add_co_u32_e32 v72, vcc, s0, v72
	v_pk_mul_f32 v[48:49], v[48:49], v[80:81] op_sel_hi:[1,0]
	s_nop 0
	v_addc_co_u32_e32 v73, vcc, 0, v73, vcc
	global_load_dwordx4 v[72:75], v[72:73], off
	s_nop 0
	global_load_dwordx4 v[76:79], v[76:77], off offset:16
	v_pk_mul_f32 v[56:57], v[56:57], v[80:81] op_sel_hi:[1,0]
	v_pk_mul_f32 v[50:51], v[50:51], v[80:81] op_sel_hi:[1,0]
	v_pk_mul_f32 v[58:59], v[58:59], v[80:81] op_sel_hi:[1,0]
	v_pk_mul_f32 v[54:55], v[54:55], v[80:81] op_sel_hi:[1,0]
	v_pk_mul_f32 v[52:53], v[52:53], v[80:81] op_sel_hi:[1,0]
	v_pk_mul_f32 v[60:61], v[60:61], v[80:81] op_sel_hi:[1,0]
	v_pk_mul_f32 v[62:63], v[62:63], v[80:81] op_sel_hi:[1,0]
	s_waitcnt vmcnt(1)
	v_pk_mul_f32 v[80:81], v[72:73], v[52:53]
	s_waitcnt vmcnt(0)
	v_pk_mul_f32 v[84:85], v[76:77], v[48:49]
	v_pk_mul_f32 v[86:87], v[78:79], v[50:51]
	v_pk_fma_f32 v[84:85], v[64:65], v[56:57], v[84:85] neg_lo:[0,0,1] neg_hi:[0,0,1]
	v_pk_mul_f32 v[56:57], v[76:77], v[56:57]
	v_pk_fma_f32 v[86:87], v[66:67], v[58:59], v[86:87] neg_lo:[0,0,1] neg_hi:[0,0,1]
	v_pk_mul_f32 v[58:59], v[78:79], v[58:59]
	v_pk_fma_f32 v[56:57], v[64:65], v[48:49], v[56:57]
	v_ashrrev_i32_e32 v48, 31, v88
	v_pk_mul_f32 v[82:83], v[74:75], v[54:55]
	v_pk_fma_f32 v[58:59], v[66:67], v[50:51], v[58:59]
	v_mul_lo_u32 v50, s10, v48
	v_mul_lo_u32 v51, s11, v88
	v_mad_u64_u32 v[48:49], s[12:13], s10, v88, 0
	v_pk_fma_f32 v[82:83], v[70:71], v[62:63], v[82:83] neg_lo:[0,0,1] neg_hi:[0,0,1]
	v_pk_fma_f32 v[80:81], v[68:69], v[60:61], v[80:81] neg_lo:[0,0,1] neg_hi:[0,0,1]
	v_pk_mul_f32 v[60:61], v[72:73], v[60:61]
	v_pk_mul_f32 v[62:63], v[74:75], v[62:63]
	v_add3_u32 v49, v49, v50, v51
	v_pk_fma_f32 v[54:55], v[70:71], v[54:55], v[62:63]
	v_pk_fma_f32 v[52:53], v[68:69], v[52:53], v[60:61]
	v_lshl_add_u64 v[60:61], v[48:49], 1, v[144:145]
	v_cvt_pk_bf16_f32 v48, v80, v81
	v_cvt_pk_bf16_f32 v49, v82, v83
	v_cvt_pk_bf16_f32 v50, v84, v85
	v_cvt_pk_bf16_f32 v51, v86, v87
	global_store_dwordx4 v[60:61], v[48:51], off
	v_add_u32_e32 v72, 0x90, v158
	s_nop 0
	v_cvt_pk_bf16_f32 v48, v52, v53
	v_cvt_pk_bf16_f32 v49, v54, v55
	v_cvt_pk_bf16_f32 v50, v56, v57
	v_cvt_pk_bf16_f32 v51, v58, v59
	global_store_dwordx4 v[60:61], v[48:51], off offset:64
	s_nop 1
	v_add_u32_e32 v48, s2, v72
	v_ashrrev_i32_e32 v49, 31, v48
	v_lshl_add_u64 v[48:49], v[48:49], 2, s[4:5]
	v_mov_b32_e32 v48, v178
	v_fmamk_f32 v48, v48, 0x3a800000, v203
	v_cmp_gt_f32_e32 vcc, s82, v48
	v_mul_f32_e32 v49, 0x4b800000, v48
	s_nop 0
	v_cndmask_b32_e32 v48, v48, v49, vcc
	v_rsq_f32_e32 v48, v48
	s_nop 0
	v_mul_f32_e32 v49, 0x45800000, v48
	v_cndmask_b32_e32 v48, v48, v49, vcc
	v_mul_f32_e32 v64, s3, v48
	v_lshlrev_b32_e32 v48, 7, v72
	v_and_b32_e32 v48, 0x3ef80, v48
	v_mov_b32_e32 v49, v187
	v_lshl_add_u64 v[56:57], v[138:139], 0, v[48:49]
	global_load_dwordx4 v[48:51], v[56:57], off offset:16
	global_load_dwordx4 v[52:55], v[56:57], off
	v_lshl_add_u64 v[60:61], v[56:57], 0, s[14:15]
	v_add_co_u32_e32 v56, vcc, s0, v56
	v_pk_mul_f32 v[32:33], v[32:33], v[64:65] op_sel_hi:[1,0]
	s_nop 0
	v_addc_co_u32_e32 v57, vcc, 0, v57, vcc
	global_load_dwordx4 v[56:59], v[56:57], off
	s_nop 0
	global_load_dwordx4 v[60:63], v[60:61], off offset:16
	v_pk_mul_f32 v[40:41], v[40:41], v[64:65] op_sel_hi:[1,0]
	v_pk_mul_f32 v[34:35], v[34:35], v[64:65] op_sel_hi:[1,0]
	v_pk_mul_f32 v[42:43], v[42:43], v[64:65] op_sel_hi:[1,0]
	v_pk_mul_f32 v[38:39], v[38:39], v[64:65] op_sel_hi:[1,0]
	v_pk_mul_f32 v[36:37], v[36:37], v[64:65] op_sel_hi:[1,0]
	v_pk_mul_f32 v[44:45], v[44:45], v[64:65] op_sel_hi:[1,0]
	v_pk_mul_f32 v[46:47], v[46:47], v[64:65] op_sel_hi:[1,0]
	s_waitcnt vmcnt(1)
; DI u32x4 pack8(f32x4 a, f32x4 b) { u32x4 w; w.x = cvtpk(a[0], a[1]); w.y = cvtpk(a[2], a[3]); w.z = cvtpk(b[0], b[1]); w.w = cvtpk(b[2], b[3]); return w; }
;   DI void operator()(const f32x4 (&acc)[2][2][4][2], const Unit& u, int wr, int wc, int fr, int fq) const {
;     ...
; #pragma unroll
;       for (int ai = 0; ai < 2; ++ai)
; #pragma unroll
;         for (int m = 0; m < 4; ++m) {
;           const int rowl = rowl0 + ai * 128 + m * 16; const int t = rowl & (SEQ - 1);
;           const float rstd = rsqrtf(ssq[row_off + rowl] * (1.f / DM) + EPSN) * sc;
;           const float* rc = rope + t * 32 + 8 * fq;
;           const f32x4 c0 = *(const f32x4*)(rc), c1 = *(const f32x4*)(rc + 4), s0 = *(const f32x4*)(rc + 65536), s1 = *(const f32x4*)(rc + 65536 + 4);
;           const f32x4 x1a = acc[ai][0][m][0] * rstd, x1b = acc[ai][0][m][1] * rstd, x2a = acc[ai][1][m][0] * rstd, x2b = acc[ai][1][m][1] * rstd;
;           const f32x4 o1a = x1a * c0 - x2a * s0, o1b = x1b * c1 - x2b * s1, o2a = x2a * c0 + x1a * s0, o2b = x2b * c1 + x1b * s1;
;           bf16_t* d = dst + (size_t)rowl * pitch + colbase + 8 * fq;
;           *(u32x4*)(d) = pack8(o1a, o1b); *(u32x4*)(d + 32) = pack8(o2a, o2b);
;           asm volatile("" ::: "memory");
;         }
	v_pk_mul_f32 v[64:65], v[56:57], v[36:37]
	s_waitcnt vmcnt(0)
	v_pk_mul_f32 v[68:69], v[60:61], v[32:33]
	v_pk_mul_f32 v[70:71], v[62:63], v[34:35]
	v_pk_fma_f32 v[68:69], v[48:49], v[40:41], v[68:69] neg_lo:[0,0,1] neg_hi:[0,0,1]
	v_pk_mul_f32 v[40:41], v[60:61], v[40:41]
	v_pk_fma_f32 v[70:71], v[50:51], v[42:43], v[70:71] neg_lo:[0,0,1] neg_hi:[0,0,1]
	v_pk_mul_f32 v[42:43], v[62:63], v[42:43]
	v_pk_fma_f32 v[40:41], v[48:49], v[32:33], v[40:41]
	v_ashrrev_i32_e32 v32, 31, v72
	v_pk_mul_f32 v[66:67], v[58:59], v[38:39]
	v_pk_fma_f32 v[42:43], v[50:51], v[34:35], v[42:43]
	v_mul_lo_u32 v34, s10, v32
	v_mul_lo_u32 v35, s11, v72
	v_mad_u64_u32 v[32:33], s[12:13], s10, v72, 0
	v_pk_fma_f32 v[66:67], v[54:55], v[46:47], v[66:67] neg_lo:[0,0,1] neg_hi:[0,0,1]
	v_pk_fma_f32 v[64:65], v[52:53], v[44:45], v[64:65] neg_lo:[0,0,1] neg_hi:[0,0,1]
	v_pk_mul_f32 v[44:45], v[56:57], v[44:45]
	v_pk_mul_f32 v[46:47], v[58:59], v[46:47]
	v_add3_u32 v33, v33, v34, v35
	v_pk_fma_f32 v[38:39], v[54:55], v[38:39], v[46:47]
	v_pk_fma_f32 v[36:37], v[52:53], v[36:37], v[44:45]
	v_lshl_add_u64 v[44:45], v[32:33], 1, v[144:145]
	v_cvt_pk_bf16_f32 v32, v64, v65
	v_cvt_pk_bf16_f32 v33, v66, v67
	v_cvt_pk_bf16_f32 v34, v68, v69
	v_cvt_pk_bf16_f32 v35, v70, v71
	global_store_dwordx4 v[44:45], v[32:35], off
	v_add_u32_e32 v56, 0xa0, v158
	s_nop 0
	v_cvt_pk_bf16_f32 v32, v36, v37
	v_cvt_pk_bf16_f32 v33, v38, v39
	v_cvt_pk_bf16_f32 v34, v40, v41
	v_cvt_pk_bf16_f32 v35, v42, v43
	global_store_dwordx4 v[44:45], v[32:35], off offset:64
	s_nop 1
	v_add_u32_e32 v32, s2, v56
	v_ashrrev_i32_e32 v33, 31, v32
	v_lshl_add_u64 v[32:33], v[32:33], 2, s[4:5]
	v_mov_b32_e32 v32, v179
	v_fmamk_f32 v32, v32, 0x3a800000, v203
	v_cmp_gt_f32_e32 vcc, s82, v32
	v_mul_f32_e32 v33, 0x4b800000, v32
	s_nop 0
	v_cndmask_b32_e32 v32, v32, v33, vcc
	v_rsq_f32_e32 v32, v32
	s_nop 0
	v_mul_f32_e32 v33, 0x45800000, v32
	v_cndmask_b32_e32 v32, v32, v33, vcc
	v_mul_f32_e32 v48, s3, v32
	v_lshlrev_b32_e32 v32, 7, v56
	v_and_b32_e32 v32, 0x3f780, v32
	v_mov_b32_e32 v33, v187
	v_lshl_add_u64 v[40:41], v[138:139], 0, v[32:33]
	global_load_dwordx4 v[32:35], v[40:41], off offset:16
	global_load_dwordx4 v[36:39], v[40:41], off
	v_lshl_add_u64 v[44:45], v[40:41], 0, s[14:15]
	v_add_co_u32_e32 v40, vcc, s0, v40
	v_pk_mul_f32 v[16:17], v[16:17], v[48:49] op_sel_hi:[1,0]
	s_nop 0
	v_addc_co_u32_e32 v41, vcc, 0, v41, vcc
	global_load_dwordx4 v[40:43], v[40:41], off
	s_nop 0
	global_load_dwordx4 v[44:47], v[44:45], off offset:16
	v_pk_mul_f32 v[24:25], v[24:25], v[48:49] op_sel_hi:[1,0]
	v_pk_mul_f32 v[18:19], v[18:19], v[48:49] op_sel_hi:[1,0]
	v_pk_mul_f32 v[26:27], v[26:27], v[48:49] op_sel_hi:[1,0]
	v_pk_mul_f32 v[22:23], v[22:23], v[48:49] op_sel_hi:[1,0]
	v_pk_mul_f32 v[20:21], v[20:21], v[48:49] op_sel_hi:[1,0]
	v_pk_mul_f32 v[28:29], v[28:29], v[48:49] op_sel_hi:[1,0]
	v_pk_mul_f32 v[30:31], v[30:31], v[48:49] op_sel_hi:[1,0]
	s_waitcnt vmcnt(1)
	v_pk_mul_f32 v[48:49], v[40:41], v[20:21]
	s_waitcnt vmcnt(0)
; DI u32x4 pack8(f32x4 a, f32x4 b) { u32x4 w; w.x = cvtpk(a[0], a[1]); w.y = cvtpk(a[2], a[3]); w.z = cvtpk(b[0], b[1]); w.w = cvtpk(b[2], b[3]); return w; }
;   DI void operator()(const f32x4 (&acc)[2][2][4][2], const Unit& u, int wr, int wc, int fr, int fq) const {
;     ...
; #pragma unroll
;       for (int ai = 0; ai < 2; ++ai)
; #pragma unroll
;         for (int m = 0; m < 4; ++m) {
;           const int rowl = rowl0 + ai * 128 + m * 16; const int t = rowl & (SEQ - 1);
;           const float rstd = rsqrtf(ssq[row_off + rowl] * (1.f / DM) + EPSN) * sc;
;           const float* rc = rope + t * 32 + 8 * fq;
;           const f32x4 c0 = *(const f32x4*)(rc), c1 = *(const f32x4*)(rc + 4), s0 = *(const f32x4*)(rc + 65536), s1 = *(const f32x4*)(rc + 65536 + 4);
;           const f32x4 x1a = acc[ai][0][m][0] * rstd, x1b = acc[ai][0][m][1] * rstd, x2a = acc[ai][1][m][0] * rstd, x2b = acc[ai][1][m][1] * rstd;
;           const f32x4 o1a = x1a * c0 - x2a * s0, o1b = x1b * c1 - x2b * s1, o2a = x2a * c0 + x1a * s0, o2b = x2b * c1 + x1b * s1;
;           bf16_t* d = dst + (size_t)rowl * pitch + colbase + 8 * fq;
;           *(u32x4*)(d) = pack8(o1a, o1b); *(u32x4*)(d + 32) = pack8(o2a, o2b);
;           asm volatile("" ::: "memory");
;         }
	v_pk_mul_f32 v[52:53], v[44:45], v[16:17]
	v_pk_mul_f32 v[54:55], v[46:47], v[18:19]
	v_pk_fma_f32 v[52:53], v[32:33], v[24:25], v[52:53] neg_lo:[0,0,1] neg_hi:[0,0,1]
	v_pk_mul_f32 v[24:25], v[44:45], v[24:25]
	v_pk_fma_f32 v[54:55], v[34:35], v[26:27], v[54:55] neg_lo:[0,0,1] neg_hi:[0,0,1]
	v_pk_mul_f32 v[26:27], v[46:47], v[26:27]
	v_pk_fma_f32 v[24:25], v[32:33], v[16:17], v[24:25]
	v_ashrrev_i32_e32 v16, 31, v56
	v_pk_mul_f32 v[50:51], v[42:43], v[22:23]
	v_pk_fma_f32 v[26:27], v[34:35], v[18:19], v[26:27]
	v_mul_lo_u32 v18, s10, v16
	v_mul_lo_u32 v19, s11, v56
	v_mad_u64_u32 v[16:17], s[12:13], s10, v56, 0
	v_pk_fma_f32 v[50:51], v[38:39], v[30:31], v[50:51] neg_lo:[0,0,1] neg_hi:[0,0,1]
	v_pk_fma_f32 v[48:49], v[36:37], v[28:29], v[48:49] neg_lo:[0,0,1] neg_hi:[0,0,1]
	v_pk_mul_f32 v[28:29], v[40:41], v[28:29]
	v_pk_mul_f32 v[30:31], v[42:43], v[30:31]
	v_add3_u32 v17, v17, v18, v19
	v_pk_fma_f32 v[22:23], v[38:39], v[22:23], v[30:31]
	v_pk_fma_f32 v[20:21], v[36:37], v[20:21], v[28:29]
	v_lshl_add_u64 v[28:29], v[16:17], 1, v[144:145]
	v_cvt_pk_bf16_f32 v16, v48, v49
	v_cvt_pk_bf16_f32 v17, v50, v51
	v_cvt_pk_bf16_f32 v18, v52, v53
	v_cvt_pk_bf16_f32 v19, v54, v55
	global_store_dwordx4 v[28:29], v[16:19], off
	v_add_u32_e32 v44, 0xb0, v158
	s_nop 0
	v_cvt_pk_bf16_f32 v16, v20, v21
	v_cvt_pk_bf16_f32 v17, v22, v23
	v_cvt_pk_bf16_f32 v18, v24, v25
	v_cvt_pk_bf16_f32 v19, v26, v27
	global_store_dwordx4 v[28:29], v[16:19], off offset:64
	s_nop 1
	v_add_u32_e32 v16, s2, v44
	v_ashrrev_i32_e32 v17, 31, v16
	v_lshl_add_u64 v[16:17], v[16:17], 2, s[4:5]
	v_mov_b32_e32 v16, v180
	v_fmamk_f32 v16, v16, 0x3a800000, v203
	v_cmp_gt_f32_e32 vcc, s82, v16
	v_mul_f32_e32 v17, 0x4b800000, v16
	s_nop 0
	v_cndmask_b32_e32 v16, v16, v17, vcc
	v_rsq_f32_e32 v16, v16
	s_nop 0
	v_mul_f32_e32 v17, 0x45800000, v16
	v_cndmask_b32_e32 v16, v16, v17, vcc
	v_mul_f32_e32 v32, s3, v16
	v_lshlrev_b32_e32 v16, 7, v44
	v_and_b32_e32 v16, 0x3ff80, v16
	v_mov_b32_e32 v17, v187
	v_lshl_add_u64 v[24:25], v[138:139], 0, v[16:17]
	global_load_dwordx4 v[16:19], v[24:25], off offset:16
	global_load_dwordx4 v[20:23], v[24:25], off
	v_lshl_add_u64 v[28:29], v[24:25], 0, s[14:15]
	v_add_co_u32_e32 v24, vcc, s0, v24
	v_pk_mul_f32 v[4:5], v[4:5], v[32:33] op_sel_hi:[1,0]
	s_nop 0
	v_addc_co_u32_e32 v25, vcc, 0, v25, vcc
	global_load_dwordx4 v[24:27], v[24:25], off
	s_nop 0
	global_load_dwordx4 v[28:31], v[28:29], off offset:16
	v_pk_mul_f32 v[34:35], v[12:13], v[32:33] op_sel_hi:[1,0]
	v_pk_mul_f32 v[36:37], v[14:15], v[32:33] op_sel_hi:[1,0]
	v_pk_mul_f32 v[38:39], v[8:9], v[32:33] op_sel_hi:[1,0]
	v_pk_mul_f32 v[40:41], v[10:11], v[32:33] op_sel_hi:[1,0]
	v_pk_mul_f32 v[6:7], v[6:7], v[32:33] op_sel_hi:[1,0]
	v_pk_mul_f32 v[42:43], v[2:3], v[32:33] op_sel_hi:[1,0]
	v_pk_mul_f32 v[32:33], v[0:1], v[32:33] op_sel_hi:[1,0]
	s_waitcnt vmcnt(1)
	v_pk_mul_f32 v[0:1], v[24:25], v[4:5]
	v_pk_mul_f32 v[2:3], v[26:27], v[6:7]
	v_pk_fma_f32 v[10:11], v[20:21], v[34:35], v[0:1] neg_lo:[0,0,1] neg_hi:[0,0,1]
	s_waitcnt vmcnt(0)
	v_pk_mul_f32 v[0:1], v[28:29], v[32:33]
	v_pk_fma_f32 v[8:9], v[22:23], v[36:37], v[2:3] neg_lo:[0,0,1] neg_hi:[0,0,1]
	v_pk_mul_f32 v[2:3], v[30:31], v[42:43]
	v_pk_fma_f32 v[14:15], v[16:17], v[38:39], v[0:1] neg_lo:[0,0,1] neg_hi:[0,0,1]
	v_pk_mul_f32 v[0:1], v[26:27], v[36:37]
	v_pk_fma_f32 v[12:13], v[18:19], v[40:41], v[2:3] neg_lo:[0,0,1] neg_hi:[0,0,1]
	v_pk_mul_f32 v[2:3], v[24:25], v[34:35]
	v_pk_fma_f32 v[0:1], v[22:23], v[6:7], v[0:1]
	v_pk_mul_f32 v[6:7], v[28:29], v[38:39]
	v_pk_fma_f32 v[2:3], v[20:21], v[4:5], v[2:3]
	v_pk_mul_f32 v[4:5], v[30:31], v[40:41]
	v_pk_fma_f32 v[6:7], v[16:17], v[32:33], v[6:7]
	v_ashrrev_i32_e32 v16, 31, v44
	v_pk_fma_f32 v[4:5], v[18:19], v[42:43], v[4:5]
	v_mul_lo_u32 v18, s10, v16
	v_mul_lo_u32 v19, s11, v44
	v_mad_u64_u32 v[16:17], s[10:11], s10, v44, 0
	v_add3_u32 v17, v17, v18, v19
	v_lshl_add_u64 v[20:21], v[16:17], 1, v[144:145]
	v_cvt_pk_bf16_f32 v16, v10, v11
	v_cvt_pk_bf16_f32 v17, v8, v9
	v_cvt_pk_bf16_f32 v18, v14, v15
	v_cvt_pk_bf16_f32 v19, v12, v13
	v_cvt_pk_bf16_f32 v8, v2, v3
	v_cvt_pk_bf16_f32 v9, v0, v1
	v_cvt_pk_bf16_f32 v10, v6, v7
	v_cvt_pk_bf16_f32 v11, v4, v5
	global_store_dwordx4 v[20:21], v[16:19], off
	global_store_dwordx4 v[20:21], v[8:11], off offset:64
	s_andn2_b64 vcc, exec, s[8:9]
	s_mov_b64 s[8:9], -1
	s_cbranch_vccnz .LBB0_620
